# in-proj epilogue store groups: 8 LDS reads in flight per group, stores behind counted lgkmcnt waits
# baseline (speedup 1.0000x reference)
.LBB0_218:
	s_and_b32 s4, s0, 0xf80
	s_cmp_gt_i32 s40, 1
	s_mov_b64 s[84:85], -1
	s_cbranch_scc0 .LBB0_249
	s_cmp_lg_u32 s40, 2
	s_cbranch_scc0 .LBB0_243
	s_cmp_gt_u32 s40, 5
	s_cbranch_scc0 .LBB0_240
	s_cmp_gt_u32 s40, 7
	s_cbranch_scc0 .LBB0_234
	s_cmp_gt_u32 s40, 9
	s_cbranch_scc0 .LBB0_228
	s_mul_i32 s6, s0, 0x600
	s_mul_hi_i32 s5, s0, 0x600
	s_add_u32 s6, s94, s6
	s_addc_u32 s5, s95, s5
	s_lshl_b32 s7, s40, 8
	s_add_u32 s84, s6, s7
	s_addc_u32 s85, s5, 0
	s_cmp_gt_u32 s40, 13
	s_mov_b64 s[86:87], -1
	s_cbranch_scc0 .LBB0_225
	v_mov_b32_e32 v10, v151
	s_mov_b64 s[6:7], 0x47fea00
	v_lshlrev_b32_e32 v0, 4, v10
	v_and_b32_e32 v0, 0xf0, v0
	v_lshl_add_u64 v[2:3], s[84:85], 0, v[0:1]
	v_ashrrev_i32_e32 v8, 4, v10
	s_movk_i32 s8, 0x110
	v_lshl_add_u64 v[6:7], v[2:3], 0, s[6:7]
	v_mad_u64_u32 v[2:3], s[6:7], v8, s8, v[0:1]
	ds_read_b128 v[2:5], v2
	s_movk_i32 s5, 0x600
	v_mad_i64_i32 v[8:9], s[6:7], v8, s5, v[6:7]
	s_mov_b64 s[86:87], 0
	v_add_u32_e32 v16, 0x100, v10
	v_ashrrev_i32_e32 v46, 4, v16
	v_mad_u64_u32 v[16:17], s[6:7], v46, s8, v[0:1]
	ds_read_b128 v[16:19], v16
	v_mad_i64_i32 v[46:47], s[6:7], v46, s5, v[6:7]
	v_add_u32_e32 v20, 0x200, v10
	v_ashrrev_i32_e32 v48, 4, v20
	v_mad_u64_u32 v[20:21], s[6:7], v48, s8, v[0:1]
	ds_read_b128 v[20:23], v20
	v_mad_i64_i32 v[48:49], s[6:7], v48, s5, v[6:7]
	v_add_u32_e32 v24, 0x300, v10
	v_ashrrev_i32_e32 v50, 4, v24
	v_mad_u64_u32 v[24:25], s[6:7], v50, s8, v[0:1]
	ds_read_b128 v[24:27], v24
	v_mad_i64_i32 v[50:51], s[6:7], v50, s5, v[6:7]
	v_add_u32_e32 v28, 0x400, v10
	v_ashrrev_i32_e32 v52, 4, v28
	v_mad_u64_u32 v[28:29], s[6:7], v52, s8, v[0:1]
	ds_read_b128 v[28:31], v28
	v_mad_i64_i32 v[52:53], s[6:7], v52, s5, v[6:7]
	v_add_u32_e32 v32, 0x500, v10
	v_ashrrev_i32_e32 v54, 4, v32
	v_mad_u64_u32 v[32:33], s[6:7], v54, s8, v[0:1]
	ds_read_b128 v[32:35], v32
	v_mad_i64_i32 v[54:55], s[6:7], v54, s5, v[6:7]
	v_add_u32_e32 v36, 0x600, v10
	v_ashrrev_i32_e32 v56, 4, v36
	v_mad_u64_u32 v[36:37], s[6:7], v56, s8, v[0:1]
	ds_read_b128 v[36:39], v36
	v_mad_i64_i32 v[56:57], s[6:7], v56, s5, v[6:7]
	v_add_u32_e32 v40, 0x700, v10
	v_ashrrev_i32_e32 v58, 4, v40
	v_mad_u64_u32 v[40:41], s[6:7], v58, s8, v[0:1]
	ds_read_b128 v[40:43], v40
	v_mad_i64_i32 v[6:7], s[6:7], v58, s5, v[6:7]
	s_waitcnt lgkmcnt(7)
	global_store_dwordx4 v[8:9], v[2:5], off
	s_waitcnt lgkmcnt(6)
	global_store_dwordx4 v[46:47], v[16:19], off
	s_waitcnt lgkmcnt(5)
	global_store_dwordx4 v[48:49], v[20:23], off
	s_waitcnt lgkmcnt(4)
	global_store_dwordx4 v[50:51], v[24:27], off
	s_waitcnt lgkmcnt(3)
	global_store_dwordx4 v[52:53], v[28:31], off
	s_waitcnt lgkmcnt(2)
	global_store_dwordx4 v[54:55], v[32:35], off
	s_waitcnt lgkmcnt(1)
	global_store_dwordx4 v[56:57], v[36:39], off
	s_waitcnt lgkmcnt(0)
	global_store_dwordx4 v[6:7], v[40:43], off
	s_nop 1
.LBB0_225:
	s_andn2_b64 vcc, exec, s[86:87]
	s_cbranch_vccnz .LBB0_227
	v_mov_b32_e32 v10, v151
	s_mov_b64 s[6:7], 0x47ff600
	v_lshlrev_b32_e32 v0, 4, v10
	v_and_b32_e32 v0, 0xf0, v0
	v_lshl_add_u64 v[2:3], s[84:85], 0, v[0:1]
	v_ashrrev_i32_e32 v8, 4, v10
	s_movk_i32 s8, 0x110
	v_lshl_add_u64 v[6:7], v[2:3], 0, s[6:7]
	v_mad_u64_u32 v[2:3], s[6:7], v8, s8, v[0:1]
	ds_read_b128 v[2:5], v2
	s_movk_i32 s5, 0x600
	v_mad_i64_i32 v[8:9], s[6:7], v8, s5, v[6:7]
	v_add_u32_e32 v16, 0x100, v10
	v_ashrrev_i32_e32 v46, 4, v16
	v_mad_u64_u32 v[16:17], s[6:7], v46, s8, v[0:1]
	ds_read_b128 v[16:19], v16
	v_mad_i64_i32 v[46:47], s[6:7], v46, s5, v[6:7]
	v_add_u32_e32 v20, 0x200, v10
	v_ashrrev_i32_e32 v48, 4, v20
	v_mad_u64_u32 v[20:21], s[6:7], v48, s8, v[0:1]
	ds_read_b128 v[20:23], v20
	v_mad_i64_i32 v[48:49], s[6:7], v48, s5, v[6:7]
	v_add_u32_e32 v24, 0x300, v10
	v_ashrrev_i32_e32 v50, 4, v24
	v_mad_u64_u32 v[24:25], s[6:7], v50, s8, v[0:1]
	ds_read_b128 v[24:27], v24
	v_mad_i64_i32 v[50:51], s[6:7], v50, s5, v[6:7]
	v_add_u32_e32 v28, 0x400, v10
	v_ashrrev_i32_e32 v52, 4, v28
	v_mad_u64_u32 v[28:29], s[6:7], v52, s8, v[0:1]
	ds_read_b128 v[28:31], v28
	v_mad_i64_i32 v[52:53], s[6:7], v52, s5, v[6:7]
	v_add_u32_e32 v32, 0x500, v10
	v_ashrrev_i32_e32 v54, 4, v32
	v_mad_u64_u32 v[32:33], s[6:7], v54, s8, v[0:1]
	ds_read_b128 v[32:35], v32
	v_mad_i64_i32 v[54:55], s[6:7], v54, s5, v[6:7]
	v_add_u32_e32 v36, 0x600, v10
	v_ashrrev_i32_e32 v56, 4, v36
	v_mad_u64_u32 v[36:37], s[6:7], v56, s8, v[0:1]
	ds_read_b128 v[36:39], v36
	v_mad_i64_i32 v[56:57], s[6:7], v56, s5, v[6:7]
	v_add_u32_e32 v40, 0x700, v10
	v_ashrrev_i32_e32 v58, 4, v40
	v_mad_u64_u32 v[40:41], s[6:7], v58, s8, v[0:1]
	ds_read_b128 v[40:43], v40
	v_mad_i64_i32 v[6:7], s[6:7], v58, s5, v[6:7]
	s_waitcnt lgkmcnt(7)
	global_store_dwordx4 v[8:9], v[2:5], off
	s_waitcnt lgkmcnt(6)
	global_store_dwordx4 v[46:47], v[16:19], off
	s_waitcnt lgkmcnt(5)
	global_store_dwordx4 v[48:49], v[20:23], off
	s_waitcnt lgkmcnt(4)
	global_store_dwordx4 v[50:51], v[24:27], off
	s_waitcnt lgkmcnt(3)
	global_store_dwordx4 v[52:53], v[28:31], off
	s_waitcnt lgkmcnt(2)
	global_store_dwordx4 v[54:55], v[32:35], off
	s_waitcnt lgkmcnt(1)
	global_store_dwordx4 v[56:57], v[36:39], off
	s_waitcnt lgkmcnt(0)
	global_store_dwordx4 v[6:7], v[40:43], off
	s_nop 1

.LBB0_228:
	s_andn2_b64 vcc, exec, s[84:85]
	s_cbranch_vccnz .LBB0_233
	s_lshl_b64 s[6:7], s[0:1], 9
	s_add_u32 s5, s94, s6
	s_addc_u32 s6, s95, s7
	s_lshl_b32 s7, s40, 8
	s_add_u32 s5, s5, s7
	s_addc_u32 s6, s6, 0
	s_add_u32 s84, s5, 0x77ff800
	s_addc_u32 s85, s6, 0
	s_mov_b64 s[86:87], -1
	s_and_b64 vcc, exec, s[44:45]
	s_cbranch_vccz .LBB0_231
	v_mov_b32_e32 v10, v151
	s_movk_i32 s5, 0x110
	v_lshlrev_b32_e32 v0, 4, v10
	v_and_b32_e32 v0, 0xf0, v0
	v_ashrrev_i32_e32 v8, 4, v10
	v_mad_u64_u32 v[2:3], s[6:7], v8, s5, v[0:1]
	ds_read_b128 v[2:5], v2
	v_ashrrev_i32_e32 v9, 31, v8
	v_lshl_add_u64 v[6:7], s[84:85], 0, v[0:1]
	v_lshlrev_b64 v[8:9], 9, v[8:9]
	v_lshl_add_u64 v[8:9], v[6:7], 0, v[8:9]
	s_mov_b64 s[86:87], 0
	v_add_u32_e32 v16, 0x100, v10
	v_ashrrev_i32_e32 v46, 4, v16
	v_mad_u64_u32 v[16:17], s[6:7], v46, s5, v[0:1]
	ds_read_b128 v[16:19], v16
	v_ashrrev_i32_e32 v47, 31, v46
	v_lshlrev_b64 v[46:47], 9, v[46:47]
	v_lshl_add_u64 v[46:47], v[6:7], 0, v[46:47]
	v_add_u32_e32 v20, 0x200, v10
	v_ashrrev_i32_e32 v48, 4, v20
	v_mad_u64_u32 v[20:21], s[6:7], v48, s5, v[0:1]
	ds_read_b128 v[20:23], v20
	v_ashrrev_i32_e32 v49, 31, v48
	v_lshlrev_b64 v[48:49], 9, v[48:49]
	v_lshl_add_u64 v[48:49], v[6:7], 0, v[48:49]
	v_add_u32_e32 v24, 0x300, v10
	v_ashrrev_i32_e32 v50, 4, v24
	v_mad_u64_u32 v[24:25], s[6:7], v50, s5, v[0:1]
	ds_read_b128 v[24:27], v24
	v_ashrrev_i32_e32 v51, 31, v50
	v_lshlrev_b64 v[50:51], 9, v[50:51]
	v_lshl_add_u64 v[50:51], v[6:7], 0, v[50:51]
	v_add_u32_e32 v28, 0x400, v10
	v_ashrrev_i32_e32 v52, 4, v28
	v_mad_u64_u32 v[28:29], s[6:7], v52, s5, v[0:1]
	ds_read_b128 v[28:31], v28
	v_ashrrev_i32_e32 v53, 31, v52
	v_lshlrev_b64 v[52:53], 9, v[52:53]
	v_lshl_add_u64 v[52:53], v[6:7], 0, v[52:53]
	v_add_u32_e32 v32, 0x500, v10
	v_ashrrev_i32_e32 v54, 4, v32
	v_mad_u64_u32 v[32:33], s[6:7], v54, s5, v[0:1]
	ds_read_b128 v[32:35], v32
	v_ashrrev_i32_e32 v55, 31, v54
	v_lshlrev_b64 v[54:55], 9, v[54:55]
	v_lshl_add_u64 v[54:55], v[6:7], 0, v[54:55]
	v_add_u32_e32 v36, 0x600, v10
	v_ashrrev_i32_e32 v56, 4, v36
	v_mad_u64_u32 v[36:37], s[6:7], v56, s5, v[0:1]
	ds_read_b128 v[36:39], v36
	v_ashrrev_i32_e32 v57, 31, v56
	v_lshlrev_b64 v[56:57], 9, v[56:57]
	v_lshl_add_u64 v[56:57], v[6:7], 0, v[56:57]
	v_add_u32_e32 v40, 0x700, v10
	v_ashrrev_i32_e32 v58, 4, v40
	v_mad_u64_u32 v[40:41], s[6:7], v58, s5, v[0:1]
	ds_read_b128 v[40:43], v40
	v_ashrrev_i32_e32 v59, 31, v58
	v_lshlrev_b64 v[58:59], 9, v[58:59]
	v_lshl_add_u64 v[6:7], v[6:7], 0, v[58:59]
	s_waitcnt lgkmcnt(7)
	global_store_dwordx4 v[8:9], v[2:5], off
	s_waitcnt lgkmcnt(6)
	global_store_dwordx4 v[46:47], v[16:19], off
	s_waitcnt lgkmcnt(5)
	global_store_dwordx4 v[48:49], v[20:23], off
	s_waitcnt lgkmcnt(4)
	global_store_dwordx4 v[50:51], v[24:27], off
	s_waitcnt lgkmcnt(3)
	global_store_dwordx4 v[52:53], v[28:31], off
	s_waitcnt lgkmcnt(2)
	global_store_dwordx4 v[54:55], v[32:35], off
	s_waitcnt lgkmcnt(1)
	global_store_dwordx4 v[56:57], v[36:39], off
	s_waitcnt lgkmcnt(0)
	global_store_dwordx4 v[6:7], v[40:43], off
	s_nop 1

.LBB0_234:
	s_andn2_b64 vcc, exec, s[84:85]
	s_cbranch_vccnz .LBB0_239
	s_lshl_b64 s[6:7], s[0:1], 9
	s_add_u32 s5, s94, s6
	s_addc_u32 s6, s95, s7
	s_lshl_b32 s7, s40, 8
	s_add_u32 s5, s5, s7
	s_addc_u32 s6, s6, 0
	s_add_u32 s84, s5, 0x6bffa00
	s_addc_u32 s85, s6, 0
	s_mov_b64 s[86:87], -1
	s_and_b64 vcc, exec, s[44:45]
	s_cbranch_vccz .LBB0_237
	v_mov_b32_e32 v10, v151
	s_movk_i32 s5, 0x110
	v_lshlrev_b32_e32 v0, 4, v10
	v_and_b32_e32 v0, 0xf0, v0
	v_ashrrev_i32_e32 v8, 4, v10
	v_mad_u64_u32 v[2:3], s[6:7], v8, s5, v[0:1]
	ds_read_b128 v[2:5], v2
	v_ashrrev_i32_e32 v9, 31, v8
	v_lshl_add_u64 v[6:7], s[84:85], 0, v[0:1]
	v_lshlrev_b64 v[8:9], 9, v[8:9]
	v_lshl_add_u64 v[8:9], v[6:7], 0, v[8:9]
	s_mov_b64 s[86:87], 0
	v_add_u32_e32 v16, 0x100, v10
	v_ashrrev_i32_e32 v46, 4, v16
	v_mad_u64_u32 v[16:17], s[6:7], v46, s5, v[0:1]
	ds_read_b128 v[16:19], v16
	v_ashrrev_i32_e32 v47, 31, v46
	v_lshlrev_b64 v[46:47], 9, v[46:47]
	v_lshl_add_u64 v[46:47], v[6:7], 0, v[46:47]
	v_add_u32_e32 v20, 0x200, v10
	v_ashrrev_i32_e32 v48, 4, v20
	v_mad_u64_u32 v[20:21], s[6:7], v48, s5, v[0:1]
	ds_read_b128 v[20:23], v20
	v_ashrrev_i32_e32 v49, 31, v48
	v_lshlrev_b64 v[48:49], 9, v[48:49]
	v_lshl_add_u64 v[48:49], v[6:7], 0, v[48:49]
	v_add_u32_e32 v24, 0x300, v10
	v_ashrrev_i32_e32 v50, 4, v24
	v_mad_u64_u32 v[24:25], s[6:7], v50, s5, v[0:1]
	ds_read_b128 v[24:27], v24
	v_ashrrev_i32_e32 v51, 31, v50
	v_lshlrev_b64 v[50:51], 9, v[50:51]
	v_lshl_add_u64 v[50:51], v[6:7], 0, v[50:51]
	v_add_u32_e32 v28, 0x400, v10
	v_ashrrev_i32_e32 v52, 4, v28
	v_mad_u64_u32 v[28:29], s[6:7], v52, s5, v[0:1]
	ds_read_b128 v[28:31], v28
	v_ashrrev_i32_e32 v53, 31, v52
	v_lshlrev_b64 v[52:53], 9, v[52:53]
	v_lshl_add_u64 v[52:53], v[6:7], 0, v[52:53]
	v_add_u32_e32 v32, 0x500, v10
	v_ashrrev_i32_e32 v54, 4, v32
	v_mad_u64_u32 v[32:33], s[6:7], v54, s5, v[0:1]
	ds_read_b128 v[32:35], v32
	v_ashrrev_i32_e32 v55, 31, v54
	v_lshlrev_b64 v[54:55], 9, v[54:55]
	v_lshl_add_u64 v[54:55], v[6:7], 0, v[54:55]
	v_add_u32_e32 v36, 0x600, v10
	v_ashrrev_i32_e32 v56, 4, v36
	v_mad_u64_u32 v[36:37], s[6:7], v56, s5, v[0:1]
	ds_read_b128 v[36:39], v36
	v_ashrrev_i32_e32 v57, 31, v56
	v_lshlrev_b64 v[56:57], 9, v[56:57]
	v_lshl_add_u64 v[56:57], v[6:7], 0, v[56:57]
	v_add_u32_e32 v40, 0x700, v10
	v_ashrrev_i32_e32 v58, 4, v40
	v_mad_u64_u32 v[40:41], s[6:7], v58, s5, v[0:1]
	ds_read_b128 v[40:43], v40
	v_ashrrev_i32_e32 v59, 31, v58
	v_lshlrev_b64 v[58:59], 9, v[58:59]
	v_lshl_add_u64 v[6:7], v[6:7], 0, v[58:59]
	s_waitcnt lgkmcnt(7)
	global_store_dwordx4 v[8:9], v[2:5], off
	s_waitcnt lgkmcnt(6)
	global_store_dwordx4 v[46:47], v[16:19], off
	s_waitcnt lgkmcnt(5)
	global_store_dwordx4 v[48:49], v[20:23], off
	s_waitcnt lgkmcnt(4)
	global_store_dwordx4 v[50:51], v[24:27], off
	s_waitcnt lgkmcnt(3)
	global_store_dwordx4 v[52:53], v[28:31], off
	s_waitcnt lgkmcnt(2)
	global_store_dwordx4 v[54:55], v[32:35], off
	s_waitcnt lgkmcnt(1)
	global_store_dwordx4 v[56:57], v[36:39], off
	s_waitcnt lgkmcnt(0)
	global_store_dwordx4 v[6:7], v[40:43], off
	s_nop 1

.LBB0_240:
	s_andn2_b64 vcc, exec, s[84:85]
	s_cbranch_vccnz .LBB0_242
	s_mul_i32 s6, s0, 0x600
	s_mul_hi_i32 s5, s0, 0x600
	s_add_u32 s6, s94, s6
	s_addc_u32 s5, s95, s5
	s_lshl_b32 s7, s40, 8
	v_mov_b32_e32 v10, v151
	s_add_u32 s6, s6, s7
	s_addc_u32 s7, s5, 0
	v_lshlrev_b32_e32 v0, 4, v10
	v_and_b32_e32 v0, 0xf0, v0
	v_lshl_add_u64 v[2:3], s[6:7], 0, v[0:1]
	s_mov_b64 s[6:7], 0x47ffc00
	v_ashrrev_i32_e32 v8, 4, v10
	s_movk_i32 s8, 0x110
	v_lshl_add_u64 v[6:7], v[2:3], 0, s[6:7]
	v_mad_u64_u32 v[2:3], s[6:7], v8, s8, v[0:1]
	ds_read_b128 v[2:5], v2
	s_movk_i32 s5, 0x600
	v_mad_i64_i32 v[8:9], s[6:7], v8, s5, v[6:7]
	v_add_u32_e32 v16, 0x100, v10
	v_ashrrev_i32_e32 v46, 4, v16
	v_mad_u64_u32 v[16:17], s[6:7], v46, s8, v[0:1]
	ds_read_b128 v[16:19], v16
	v_mad_i64_i32 v[46:47], s[6:7], v46, s5, v[6:7]
	v_add_u32_e32 v20, 0x200, v10
	v_ashrrev_i32_e32 v48, 4, v20
	v_mad_u64_u32 v[20:21], s[6:7], v48, s8, v[0:1]
	ds_read_b128 v[20:23], v20
	v_mad_i64_i32 v[48:49], s[6:7], v48, s5, v[6:7]
	v_add_u32_e32 v24, 0x300, v10
	v_ashrrev_i32_e32 v50, 4, v24
	v_mad_u64_u32 v[24:25], s[6:7], v50, s8, v[0:1]
	ds_read_b128 v[24:27], v24
	v_mad_i64_i32 v[50:51], s[6:7], v50, s5, v[6:7]
	v_add_u32_e32 v28, 0x400, v10
	v_ashrrev_i32_e32 v52, 4, v28
	v_mad_u64_u32 v[28:29], s[6:7], v52, s8, v[0:1]
	ds_read_b128 v[28:31], v28
	v_mad_i64_i32 v[52:53], s[6:7], v52, s5, v[6:7]
	v_add_u32_e32 v32, 0x500, v10
	v_ashrrev_i32_e32 v54, 4, v32
	v_mad_u64_u32 v[32:33], s[6:7], v54, s8, v[0:1]
	ds_read_b128 v[32:35], v32
	v_mad_i64_i32 v[54:55], s[6:7], v54, s5, v[6:7]
	v_add_u32_e32 v36, 0x600, v10
	v_ashrrev_i32_e32 v56, 4, v36
	v_mad_u64_u32 v[36:37], s[6:7], v56, s8, v[0:1]
	ds_read_b128 v[36:39], v36
	v_mad_i64_i32 v[56:57], s[6:7], v56, s5, v[6:7]
	v_add_u32_e32 v40, 0x700, v10
	v_ashrrev_i32_e32 v58, 4, v40
	v_mad_u64_u32 v[40:41], s[6:7], v58, s8, v[0:1]
	ds_read_b128 v[40:43], v40
	v_mad_i64_i32 v[6:7], s[6:7], v58, s5, v[6:7]
	s_waitcnt lgkmcnt(7)
	global_store_dwordx4 v[8:9], v[2:5], off
	s_waitcnt lgkmcnt(6)
	global_store_dwordx4 v[46:47], v[16:19], off
	s_waitcnt lgkmcnt(5)
	global_store_dwordx4 v[48:49], v[20:23], off
	s_waitcnt lgkmcnt(4)
	global_store_dwordx4 v[50:51], v[24:27], off
	s_waitcnt lgkmcnt(3)
	global_store_dwordx4 v[52:53], v[28:31], off
	s_waitcnt lgkmcnt(2)
	global_store_dwordx4 v[54:55], v[32:35], off
	s_waitcnt lgkmcnt(1)
	global_store_dwordx4 v[56:57], v[36:39], off
	s_waitcnt lgkmcnt(0)
	global_store_dwordx4 v[6:7], v[40:43], off
	s_nop 1

.LBB0_243:
	s_andn2_b64 vcc, exec, s[84:85]
	s_cbranch_vccnz .LBB0_248
	s_lshl_b64 s[6:7], s[0:1], 8
	v_readlane_b32 s5, v253, 54
	s_add_u32 s84, s5, s6
	v_readlane_b32 s5, v253, 55
	s_addc_u32 s85, s5, s7
	s_mov_b64 s[86:87], -1
	s_and_b64 vcc, exec, s[44:45]
	s_cbranch_vccz .LBB0_246
	v_mov_b32_e32 v10, v151
	s_movk_i32 s5, 0x110
	v_lshlrev_b32_e32 v0, 4, v10
	v_and_b32_e32 v0, 0xf0, v0
	v_ashrrev_i32_e32 v8, 4, v10
	v_mad_u64_u32 v[2:3], s[6:7], v8, s5, v[0:1]
	ds_read_b128 v[2:5], v2
	v_ashrrev_i32_e32 v9, 31, v8
	v_lshl_add_u64 v[6:7], s[84:85], 0, v[0:1]
	v_lshlrev_b64 v[8:9], 8, v[8:9]
	v_lshl_add_u64 v[8:9], v[6:7], 0, v[8:9]
	s_mov_b64 s[86:87], 0
	v_add_u32_e32 v16, 0x100, v10
	v_ashrrev_i32_e32 v46, 4, v16
	v_mad_u64_u32 v[16:17], s[6:7], v46, s5, v[0:1]
	ds_read_b128 v[16:19], v16
	v_ashrrev_i32_e32 v47, 31, v46
	v_lshlrev_b64 v[46:47], 8, v[46:47]
	v_lshl_add_u64 v[46:47], v[6:7], 0, v[46:47]
	v_add_u32_e32 v20, 0x200, v10
	v_ashrrev_i32_e32 v48, 4, v20
	v_mad_u64_u32 v[20:21], s[6:7], v48, s5, v[0:1]
	ds_read_b128 v[20:23], v20
	v_ashrrev_i32_e32 v49, 31, v48
	v_lshlrev_b64 v[48:49], 8, v[48:49]
	v_lshl_add_u64 v[48:49], v[6:7], 0, v[48:49]
	v_add_u32_e32 v24, 0x300, v10
	v_ashrrev_i32_e32 v50, 4, v24
	v_mad_u64_u32 v[24:25], s[6:7], v50, s5, v[0:1]
	ds_read_b128 v[24:27], v24
	v_ashrrev_i32_e32 v51, 31, v50
	v_lshlrev_b64 v[50:51], 8, v[50:51]
	v_lshl_add_u64 v[50:51], v[6:7], 0, v[50:51]
	v_add_u32_e32 v28, 0x400, v10
	v_ashrrev_i32_e32 v52, 4, v28
	v_mad_u64_u32 v[28:29], s[6:7], v52, s5, v[0:1]
	ds_read_b128 v[28:31], v28
	v_ashrrev_i32_e32 v53, 31, v52
	v_lshlrev_b64 v[52:53], 8, v[52:53]
	v_lshl_add_u64 v[52:53], v[6:7], 0, v[52:53]
	v_add_u32_e32 v32, 0x500, v10
	v_ashrrev_i32_e32 v54, 4, v32
	v_mad_u64_u32 v[32:33], s[6:7], v54, s5, v[0:1]
	ds_read_b128 v[32:35], v32
	v_ashrrev_i32_e32 v55, 31, v54
	v_lshlrev_b64 v[54:55], 8, v[54:55]
	v_lshl_add_u64 v[54:55], v[6:7], 0, v[54:55]
	v_add_u32_e32 v36, 0x600, v10
	v_ashrrev_i32_e32 v56, 4, v36
	v_mad_u64_u32 v[36:37], s[6:7], v56, s5, v[0:1]
	ds_read_b128 v[36:39], v36
	v_ashrrev_i32_e32 v57, 31, v56
	v_lshlrev_b64 v[56:57], 8, v[56:57]
	v_lshl_add_u64 v[56:57], v[6:7], 0, v[56:57]
	v_add_u32_e32 v40, 0x700, v10
	v_ashrrev_i32_e32 v58, 4, v40
	v_mad_u64_u32 v[40:41], s[6:7], v58, s5, v[0:1]
	ds_read_b128 v[40:43], v40
	v_ashrrev_i32_e32 v59, 31, v58
	v_lshlrev_b64 v[58:59], 8, v[58:59]
	v_lshl_add_u64 v[6:7], v[6:7], 0, v[58:59]
	s_waitcnt lgkmcnt(7)
	global_store_dwordx4 v[8:9], v[2:5], off
	s_waitcnt lgkmcnt(6)
	global_store_dwordx4 v[46:47], v[16:19], off
	s_waitcnt lgkmcnt(5)
	global_store_dwordx4 v[48:49], v[20:23], off
	s_waitcnt lgkmcnt(4)
	global_store_dwordx4 v[50:51], v[24:27], off
	s_waitcnt lgkmcnt(3)
	global_store_dwordx4 v[52:53], v[28:31], off
	s_waitcnt lgkmcnt(2)
	global_store_dwordx4 v[54:55], v[32:35], off
	s_waitcnt lgkmcnt(1)
	global_store_dwordx4 v[56:57], v[36:39], off
	s_waitcnt lgkmcnt(0)
	global_store_dwordx4 v[6:7], v[40:43], off
	s_nop 1

.LBB0_249:
	s_andn2_b64 vcc, exec, s[84:85]
	s_cbranch_vccnz .LBB0_254
	s_lshl_b64 s[6:7], s[0:1], 9
	v_readlane_b32 s8, v253, 34
	v_readlane_b32 s9, v253, 35
	s_add_u32 s5, s8, s6
	s_addc_u32 s8, s9, s7
	s_lshl_b32 s6, s40, 7
	s_ashr_i32 s7, s6, 31
	s_lshl_b64 s[6:7], s[6:7], 1
	s_add_u32 s84, s5, s6
	s_addc_u32 s85, s8, s7
	s_mov_b64 s[86:87], -1
	s_and_b64 vcc, exec, s[44:45]
	s_cbranch_vccz .LBB0_252
	v_mov_b32_e32 v10, v151
	s_movk_i32 s5, 0x110
	v_lshlrev_b32_e32 v0, 4, v10
	v_and_b32_e32 v0, 0xf0, v0
	v_ashrrev_i32_e32 v8, 4, v10
	v_mad_u64_u32 v[2:3], s[6:7], v8, s5, v[0:1]
	ds_read_b128 v[2:5], v2
	v_ashrrev_i32_e32 v9, 31, v8
	v_lshl_add_u64 v[6:7], s[84:85], 0, v[0:1]
	v_lshlrev_b64 v[8:9], 9, v[8:9]
	v_lshl_add_u64 v[8:9], v[6:7], 0, v[8:9]
	s_mov_b64 s[86:87], 0
	v_add_u32_e32 v16, 0x100, v10
	v_ashrrev_i32_e32 v46, 4, v16
	v_mad_u64_u32 v[16:17], s[6:7], v46, s5, v[0:1]
	ds_read_b128 v[16:19], v16
	v_ashrrev_i32_e32 v47, 31, v46
	v_lshlrev_b64 v[46:47], 9, v[46:47]
	v_lshl_add_u64 v[46:47], v[6:7], 0, v[46:47]
	v_add_u32_e32 v20, 0x200, v10
	v_ashrrev_i32_e32 v48, 4, v20
	v_mad_u64_u32 v[20:21], s[6:7], v48, s5, v[0:1]
	ds_read_b128 v[20:23], v20
	v_ashrrev_i32_e32 v49, 31, v48
	v_lshlrev_b64 v[48:49], 9, v[48:49]
	v_lshl_add_u64 v[48:49], v[6:7], 0, v[48:49]
	v_add_u32_e32 v24, 0x300, v10
	v_ashrrev_i32_e32 v50, 4, v24
	v_mad_u64_u32 v[24:25], s[6:7], v50, s5, v[0:1]
	ds_read_b128 v[24:27], v24
	v_ashrrev_i32_e32 v51, 31, v50
	v_lshlrev_b64 v[50:51], 9, v[50:51]
	v_lshl_add_u64 v[50:51], v[6:7], 0, v[50:51]
	v_add_u32_e32 v28, 0x400, v10
	v_ashrrev_i32_e32 v52, 4, v28
	v_mad_u64_u32 v[28:29], s[6:7], v52, s5, v[0:1]
	ds_read_b128 v[28:31], v28
	v_ashrrev_i32_e32 v53, 31, v52
	v_lshlrev_b64 v[52:53], 9, v[52:53]
	v_lshl_add_u64 v[52:53], v[6:7], 0, v[52:53]
	v_add_u32_e32 v32, 0x500, v10
	v_ashrrev_i32_e32 v54, 4, v32
	v_mad_u64_u32 v[32:33], s[6:7], v54, s5, v[0:1]
	ds_read_b128 v[32:35], v32
	v_ashrrev_i32_e32 v55, 31, v54
	v_lshlrev_b64 v[54:55], 9, v[54:55]
	v_lshl_add_u64 v[54:55], v[6:7], 0, v[54:55]
	v_add_u32_e32 v36, 0x600, v10
	v_ashrrev_i32_e32 v56, 4, v36
	v_mad_u64_u32 v[36:37], s[6:7], v56, s5, v[0:1]
	ds_read_b128 v[36:39], v36
	v_ashrrev_i32_e32 v57, 31, v56
	v_lshlrev_b64 v[56:57], 9, v[56:57]
	v_lshl_add_u64 v[56:57], v[6:7], 0, v[56:57]
	v_add_u32_e32 v40, 0x700, v10
	v_ashrrev_i32_e32 v58, 4, v40
	v_mad_u64_u32 v[40:41], s[6:7], v58, s5, v[0:1]
	ds_read_b128 v[40:43], v40
	v_ashrrev_i32_e32 v59, 31, v58
	v_lshlrev_b64 v[58:59], 9, v[58:59]
	v_lshl_add_u64 v[6:7], v[6:7], 0, v[58:59]
	s_waitcnt lgkmcnt(7)
	global_store_dwordx4 v[8:9], v[2:5], off
	s_waitcnt lgkmcnt(6)
	global_store_dwordx4 v[46:47], v[16:19], off
	s_waitcnt lgkmcnt(5)
	global_store_dwordx4 v[48:49], v[20:23], off
	s_waitcnt lgkmcnt(4)
	global_store_dwordx4 v[50:51], v[24:27], off
	s_waitcnt lgkmcnt(3)
	global_store_dwordx4 v[52:53], v[28:31], off
	s_waitcnt lgkmcnt(2)
	global_store_dwordx4 v[54:55], v[32:35], off
	s_waitcnt lgkmcnt(1)
	global_store_dwordx4 v[56:57], v[36:39], off
	s_waitcnt lgkmcnt(0)
	global_store_dwordx4 v[6:7], v[40:43], off
	s_nop 1

.LBB0_272:
	s_cmp_gt_i32 s40, 11
	s_mov_b64 s[28:29], -1
	s_cbranch_scc0 .LBB0_282
	s_cmp_gt_u32 s40, 19
	s_cbranch_scc0 .LBB0_279
	s_cmp_gt_u32 s40, 21
	s_cbranch_scc0 .LBB0_276
	s_sub_i32 s4, s40, 22
	s_mul_hi_u32 s5, s4, 0x600000
	s_mul_i32 s4, s4, 0x600000
	v_readlane_b32 s6, v253, 48
	s_add_u32 s6, s6, s4
	v_readlane_b32 s4, v253, 49
	s_addc_u32 s7, s4, s5
	s_lshl_b64 s[4:5], s[0:1], 1
	v_mov_b32_e32 v10, v151
	s_add_u32 s4, s6, s4
	s_addc_u32 s5, s7, s5
	v_lshlrev_b32_e32 v0, 4, v10
	v_and_b32_e32 v0, 0xf0, v0
	v_ashrrev_i32_e32 v8, 4, v10
	s_movk_i32 s6, 0x110
	v_lshl_add_u64 v[6:7], s[4:5], 0, v[0:1]
	v_mad_u64_u32 v[2:3], s[4:5], v8, s6, v[0:1]
	ds_read_b128 v[2:5], v2
	s_mov_b32 s7, 0xc000
	v_mad_i64_i32 v[8:9], s[4:5], v8, s7, v[6:7]
	s_mov_b64 s[28:29], 0
	v_add_u32_e32 v16, 0x100, v10
	v_ashrrev_i32_e32 v46, 4, v16
	v_mad_u64_u32 v[16:17], s[4:5], v46, s6, v[0:1]
	ds_read_b128 v[16:19], v16
	v_mad_i64_i32 v[46:47], s[4:5], v46, s7, v[6:7]
	v_add_u32_e32 v20, 0x200, v10
	v_ashrrev_i32_e32 v48, 4, v20
	v_mad_u64_u32 v[20:21], s[4:5], v48, s6, v[0:1]
	ds_read_b128 v[20:23], v20
	v_mad_i64_i32 v[48:49], s[4:5], v48, s7, v[6:7]
	v_add_u32_e32 v24, 0x300, v10
	v_ashrrev_i32_e32 v50, 4, v24
	v_mad_u64_u32 v[24:25], s[4:5], v50, s6, v[0:1]
	ds_read_b128 v[24:27], v24
	v_mad_i64_i32 v[50:51], s[4:5], v50, s7, v[6:7]
	v_add_u32_e32 v28, 0x400, v10
	v_ashrrev_i32_e32 v52, 4, v28
	v_mad_u64_u32 v[28:29], s[4:5], v52, s6, v[0:1]
	ds_read_b128 v[28:31], v28
	v_mad_i64_i32 v[52:53], s[4:5], v52, s7, v[6:7]
	v_add_u32_e32 v32, 0x500, v10
	v_ashrrev_i32_e32 v54, 4, v32
	v_mad_u64_u32 v[32:33], s[4:5], v54, s6, v[0:1]
	ds_read_b128 v[32:35], v32
	v_mad_i64_i32 v[54:55], s[4:5], v54, s7, v[6:7]
	v_add_u32_e32 v36, 0x600, v10
	v_ashrrev_i32_e32 v56, 4, v36
	v_mad_u64_u32 v[36:37], s[4:5], v56, s6, v[0:1]
	ds_read_b128 v[36:39], v36
	v_mad_i64_i32 v[56:57], s[4:5], v56, s7, v[6:7]
	v_add_u32_e32 v40, 0x700, v10
	v_ashrrev_i32_e32 v58, 4, v40
	v_mad_u64_u32 v[40:41], s[4:5], v58, s6, v[0:1]
	ds_read_b128 v[40:43], v40
	v_mad_i64_i32 v[6:7], s[4:5], v58, s7, v[6:7]
	s_waitcnt lgkmcnt(7)
	global_store_dwordx4 v[8:9], v[2:5], off
	s_waitcnt lgkmcnt(6)
	global_store_dwordx4 v[46:47], v[16:19], off
	s_waitcnt lgkmcnt(5)
	global_store_dwordx4 v[48:49], v[20:23], off
	s_waitcnt lgkmcnt(4)
	global_store_dwordx4 v[50:51], v[24:27], off
	s_waitcnt lgkmcnt(3)
	global_store_dwordx4 v[52:53], v[28:31], off
	s_waitcnt lgkmcnt(2)
	global_store_dwordx4 v[54:55], v[32:35], off
	s_waitcnt lgkmcnt(1)
	global_store_dwordx4 v[56:57], v[36:39], off
	s_waitcnt lgkmcnt(0)
	global_store_dwordx4 v[6:7], v[40:43], off
	s_nop 1
.LBB0_276:
	s_andn2_b64 vcc, exec, s[28:29]
	s_cbranch_vccnz .LBB0_278
	s_sub_i32 s4, s40, 20
	s_mul_hi_u32 s5, s4, 0x600000
	s_mul_i32 s4, s4, 0x600000
	v_readlane_b32 s6, v253, 50
	s_add_u32 s6, s6, s4
	v_readlane_b32 s4, v253, 51
	s_addc_u32 s7, s4, s5
	s_lshl_b64 s[4:5], s[0:1], 1
	v_mov_b32_e32 v10, v151
	s_add_u32 s4, s6, s4
	s_addc_u32 s5, s7, s5
	v_lshlrev_b32_e32 v0, 4, v10
	v_and_b32_e32 v0, 0xf0, v0
	v_ashrrev_i32_e32 v8, 4, v10
	s_movk_i32 s6, 0x110
	v_lshl_add_u64 v[6:7], s[4:5], 0, v[0:1]
	v_mad_u64_u32 v[2:3], s[4:5], v8, s6, v[0:1]
	ds_read_b128 v[2:5], v2
	s_mov_b32 s7, 0xc000
	v_mad_i64_i32 v[8:9], s[4:5], v8, s7, v[6:7]
	v_add_u32_e32 v16, 0x100, v10
	v_ashrrev_i32_e32 v46, 4, v16
	v_mad_u64_u32 v[16:17], s[4:5], v46, s6, v[0:1]
	ds_read_b128 v[16:19], v16
	v_mad_i64_i32 v[46:47], s[4:5], v46, s7, v[6:7]
	v_add_u32_e32 v20, 0x200, v10
	v_ashrrev_i32_e32 v48, 4, v20
	v_mad_u64_u32 v[20:21], s[4:5], v48, s6, v[0:1]
	ds_read_b128 v[20:23], v20
	v_mad_i64_i32 v[48:49], s[4:5], v48, s7, v[6:7]
	v_add_u32_e32 v24, 0x300, v10
	v_ashrrev_i32_e32 v50, 4, v24
	v_mad_u64_u32 v[24:25], s[4:5], v50, s6, v[0:1]
	ds_read_b128 v[24:27], v24
	v_mad_i64_i32 v[50:51], s[4:5], v50, s7, v[6:7]
	v_add_u32_e32 v28, 0x400, v10
	v_ashrrev_i32_e32 v52, 4, v28
	v_mad_u64_u32 v[28:29], s[4:5], v52, s6, v[0:1]
	ds_read_b128 v[28:31], v28
	v_mad_i64_i32 v[52:53], s[4:5], v52, s7, v[6:7]
	v_add_u32_e32 v32, 0x500, v10
	v_ashrrev_i32_e32 v54, 4, v32
	v_mad_u64_u32 v[32:33], s[4:5], v54, s6, v[0:1]
	ds_read_b128 v[32:35], v32
	v_mad_i64_i32 v[54:55], s[4:5], v54, s7, v[6:7]
	v_add_u32_e32 v36, 0x600, v10
	v_ashrrev_i32_e32 v56, 4, v36
	v_mad_u64_u32 v[36:37], s[4:5], v56, s6, v[0:1]
	ds_read_b128 v[36:39], v36
	v_mad_i64_i32 v[56:57], s[4:5], v56, s7, v[6:7]
	v_add_u32_e32 v40, 0x700, v10
	v_ashrrev_i32_e32 v58, 4, v40
	v_mad_u64_u32 v[40:41], s[4:5], v58, s6, v[0:1]
	ds_read_b128 v[40:43], v40
	v_mad_i64_i32 v[6:7], s[4:5], v58, s7, v[6:7]
	s_waitcnt lgkmcnt(7)
	global_store_dwordx4 v[8:9], v[2:5], off
	s_waitcnt lgkmcnt(6)
	global_store_dwordx4 v[46:47], v[16:19], off
	s_waitcnt lgkmcnt(5)
	global_store_dwordx4 v[48:49], v[20:23], off
	s_waitcnt lgkmcnt(4)
	global_store_dwordx4 v[50:51], v[24:27], off
	s_waitcnt lgkmcnt(3)
	global_store_dwordx4 v[52:53], v[28:31], off
	s_waitcnt lgkmcnt(2)
	global_store_dwordx4 v[54:55], v[32:35], off
	s_waitcnt lgkmcnt(1)
	global_store_dwordx4 v[56:57], v[36:39], off
	s_waitcnt lgkmcnt(0)
	global_store_dwordx4 v[6:7], v[40:43], off
	s_nop 1

.LBB0_279:
	s_andn2_b64 vcc, exec, s[28:29]
	s_cbranch_vccnz .LBB0_281
	s_mul_i32 s50, s40, 0x300000
	s_lshl_b64 s[4:5], s[50:51], 1
	s_add_u32 s6, s94, s4
	s_addc_u32 s7, s95, s5
	s_lshl_b64 s[4:5], s[0:1], 1
	v_mov_b32_e32 v10, v151
	s_add_u32 s4, s6, s4
	s_addc_u32 s5, s7, s5
	v_lshlrev_b32_e32 v0, 4, v10
	v_and_b32_e32 v0, 0xf0, v0
	v_lshl_add_u64 v[2:3], s[4:5], 0, v[0:1]
	s_mov_b64 s[4:5], 0x3c00000
	v_ashrrev_i32_e32 v8, 4, v10
	s_movk_i32 s6, 0x110
	v_lshl_add_u64 v[6:7], v[2:3], 0, s[4:5]
	v_mad_u64_u32 v[2:3], s[4:5], v8, s6, v[0:1]
	ds_read_b128 v[2:5], v2
	s_mov_b32 s7, 0xc000
	v_mad_i64_i32 v[8:9], s[4:5], v8, s7, v[6:7]
	s_movk_i32 s50, 0x3000
	v_add_u32_e32 v16, 0x100, v10
	v_ashrrev_i32_e32 v46, 4, v16
	v_mad_u64_u32 v[16:17], s[4:5], v46, s6, v[0:1]
	ds_read_b128 v[16:19], v16
	v_mad_i64_i32 v[46:47], s[4:5], v46, s7, v[6:7]
	v_add_u32_e32 v20, 0x200, v10
	v_ashrrev_i32_e32 v48, 4, v20
	v_mad_u64_u32 v[20:21], s[4:5], v48, s6, v[0:1]
	ds_read_b128 v[20:23], v20
	v_mad_i64_i32 v[48:49], s[4:5], v48, s7, v[6:7]
	v_add_u32_e32 v24, 0x300, v10
	v_ashrrev_i32_e32 v50, 4, v24
	v_mad_u64_u32 v[24:25], s[4:5], v50, s6, v[0:1]
	ds_read_b128 v[24:27], v24
	v_mad_i64_i32 v[50:51], s[4:5], v50, s7, v[6:7]
	v_add_u32_e32 v28, 0x400, v10
	v_ashrrev_i32_e32 v52, 4, v28
	v_mad_u64_u32 v[28:29], s[4:5], v52, s6, v[0:1]
	ds_read_b128 v[28:31], v28
	v_mad_i64_i32 v[52:53], s[4:5], v52, s7, v[6:7]
	v_add_u32_e32 v32, 0x500, v10
	v_ashrrev_i32_e32 v54, 4, v32
	v_mad_u64_u32 v[32:33], s[4:5], v54, s6, v[0:1]
	ds_read_b128 v[32:35], v32
	v_mad_i64_i32 v[54:55], s[4:5], v54, s7, v[6:7]
	v_add_u32_e32 v36, 0x600, v10
	v_ashrrev_i32_e32 v56, 4, v36
	v_mad_u64_u32 v[36:37], s[4:5], v56, s6, v[0:1]
	ds_read_b128 v[36:39], v36
	v_mad_i64_i32 v[56:57], s[4:5], v56, s7, v[6:7]
	v_add_u32_e32 v40, 0x700, v10
	v_ashrrev_i32_e32 v58, 4, v40
	v_mad_u64_u32 v[40:41], s[4:5], v58, s6, v[0:1]
	ds_read_b128 v[40:43], v40
	v_mad_i64_i32 v[6:7], s[4:5], v58, s7, v[6:7]
	s_waitcnt lgkmcnt(7)
	global_store_dwordx4 v[8:9], v[2:5], off
	s_waitcnt lgkmcnt(6)
	global_store_dwordx4 v[46:47], v[16:19], off
	s_waitcnt lgkmcnt(5)
	global_store_dwordx4 v[48:49], v[20:23], off
	s_waitcnt lgkmcnt(4)
	global_store_dwordx4 v[50:51], v[24:27], off
	s_waitcnt lgkmcnt(3)
	global_store_dwordx4 v[52:53], v[28:31], off
	s_waitcnt lgkmcnt(2)
	global_store_dwordx4 v[54:55], v[32:35], off
	s_waitcnt lgkmcnt(1)
	global_store_dwordx4 v[56:57], v[36:39], off
	s_waitcnt lgkmcnt(0)
	global_store_dwordx4 v[6:7], v[40:43], off
	s_nop 1

.LBB0_282:
	s_andn2_b64 vcc, exec, s[28:29]
	s_cbranch_vccnz .LBB0_284
	s_mul_i32 s4, s40, 0x300000
	s_ashr_i32 s5, s4, 31
	s_lshl_b64 s[4:5], s[4:5], 1
	s_add_u32 s6, s94, s4
	s_addc_u32 s7, s95, s5
	s_lshl_b64 s[4:5], s[0:1], 1
	v_mov_b32_e32 v10, v151
	s_add_u32 s4, s6, s4
	s_addc_u32 s5, s7, s5
	v_lshlrev_b32_e32 v0, 4, v10
	v_and_b32_e32 v0, 0xf0, v0
	v_lshl_add_u64 v[2:3], s[4:5], 0, v[0:1]
	s_mov_b64 s[4:5], 0x4800000
	v_ashrrev_i32_e32 v8, 4, v10
	s_movk_i32 s6, 0x110
	v_lshl_add_u64 v[6:7], v[2:3], 0, s[4:5]
	v_mad_u64_u32 v[2:3], s[4:5], v8, s6, v[0:1]
	ds_read_b128 v[2:5], v2
	s_mov_b32 s7, 0xc000
	v_mad_i64_i32 v[8:9], s[4:5], v8, s7, v[6:7]
	v_add_u32_e32 v16, 0x100, v10
	v_ashrrev_i32_e32 v46, 4, v16
	v_mad_u64_u32 v[16:17], s[4:5], v46, s6, v[0:1]
	ds_read_b128 v[16:19], v16
	v_mad_i64_i32 v[46:47], s[4:5], v46, s7, v[6:7]
	v_add_u32_e32 v20, 0x200, v10
	v_ashrrev_i32_e32 v48, 4, v20
	v_mad_u64_u32 v[20:21], s[4:5], v48, s6, v[0:1]
	ds_read_b128 v[20:23], v20
	v_mad_i64_i32 v[48:49], s[4:5], v48, s7, v[6:7]
	v_add_u32_e32 v24, 0x300, v10
	v_ashrrev_i32_e32 v50, 4, v24
	v_mad_u64_u32 v[24:25], s[4:5], v50, s6, v[0:1]
	ds_read_b128 v[24:27], v24
	v_mad_i64_i32 v[50:51], s[4:5], v50, s7, v[6:7]
	v_add_u32_e32 v28, 0x400, v10
	v_ashrrev_i32_e32 v52, 4, v28
	v_mad_u64_u32 v[28:29], s[4:5], v52, s6, v[0:1]
	ds_read_b128 v[28:31], v28
	v_mad_i64_i32 v[52:53], s[4:5], v52, s7, v[6:7]
	v_add_u32_e32 v32, 0x500, v10
	v_ashrrev_i32_e32 v54, 4, v32
	v_mad_u64_u32 v[32:33], s[4:5], v54, s6, v[0:1]
	ds_read_b128 v[32:35], v32
	v_mad_i64_i32 v[54:55], s[4:5], v54, s7, v[6:7]
	v_add_u32_e32 v36, 0x600, v10
	v_ashrrev_i32_e32 v56, 4, v36
	v_mad_u64_u32 v[36:37], s[4:5], v56, s6, v[0:1]
	ds_read_b128 v[36:39], v36
	v_mad_i64_i32 v[56:57], s[4:5], v56, s7, v[6:7]
	v_add_u32_e32 v40, 0x700, v10
	v_ashrrev_i32_e32 v58, 4, v40
	v_mad_u64_u32 v[40:41], s[4:5], v58, s6, v[0:1]
	ds_read_b128 v[40:43], v40
	v_mad_i64_i32 v[6:7], s[4:5], v58, s7, v[6:7]
	s_waitcnt lgkmcnt(7)
	global_store_dwordx4 v[8:9], v[2:5], off
	s_waitcnt lgkmcnt(6)
	global_store_dwordx4 v[46:47], v[16:19], off
	s_waitcnt lgkmcnt(5)
	global_store_dwordx4 v[48:49], v[20:23], off
	s_waitcnt lgkmcnt(4)
	global_store_dwordx4 v[50:51], v[24:27], off
	s_waitcnt lgkmcnt(3)
	global_store_dwordx4 v[52:53], v[28:31], off
	s_waitcnt lgkmcnt(2)
	global_store_dwordx4 v[54:55], v[32:35], off
	s_waitcnt lgkmcnt(1)
	global_store_dwordx4 v[56:57], v[36:39], off
	s_waitcnt lgkmcnt(0)
	global_store_dwordx4 v[6:7], v[40:43], off
	s_nop 1

.LBB0_285:
	s_lshl_b64 s[0:1], s[0:1], 1
	v_readlane_b32 s4, v253, 52
	v_mov_b32_e32 v10, v151
	s_add_u32 s0, s4, s0
	v_readlane_b32 s4, v253, 53
	s_addc_u32 s1, s4, s1
	v_lshlrev_b32_e32 v0, 4, v10
	v_and_b32_e32 v0, 0xf0, v0
	v_ashrrev_i32_e32 v8, 4, v10
	s_movk_i32 s4, 0x110
	v_lshl_add_u64 v[6:7], s[0:1], 0, v[0:1]
	v_mad_u64_u32 v[2:3], s[0:1], v8, s4, v[0:1]
	ds_read_b128 v[2:5], v2
	s_mov_b32 s5, 0xc000
	v_mad_i64_i32 v[8:9], s[0:1], v8, s5, v[6:7]
	v_add_u32_e32 v16, 0x100, v10
	v_ashrrev_i32_e32 v46, 4, v16
	v_mad_u64_u32 v[16:17], s[0:1], v46, s4, v[0:1]
	ds_read_b128 v[16:19], v16
	v_mad_i64_i32 v[46:47], s[0:1], v46, s5, v[6:7]
	v_add_u32_e32 v20, 0x200, v10
	v_ashrrev_i32_e32 v48, 4, v20
	v_mad_u64_u32 v[20:21], s[0:1], v48, s4, v[0:1]
	ds_read_b128 v[20:23], v20
	v_mad_i64_i32 v[48:49], s[0:1], v48, s5, v[6:7]
	v_add_u32_e32 v24, 0x300, v10
	v_ashrrev_i32_e32 v50, 4, v24
	v_mad_u64_u32 v[24:25], s[0:1], v50, s4, v[0:1]
	ds_read_b128 v[24:27], v24
	v_mad_i64_i32 v[50:51], s[0:1], v50, s5, v[6:7]
	v_add_u32_e32 v28, 0x400, v10
	v_ashrrev_i32_e32 v52, 4, v28
	v_mad_u64_u32 v[28:29], s[0:1], v52, s4, v[0:1]
	ds_read_b128 v[28:31], v28
	v_mad_i64_i32 v[52:53], s[0:1], v52, s5, v[6:7]
	v_add_u32_e32 v32, 0x500, v10
	v_ashrrev_i32_e32 v54, 4, v32
	v_mad_u64_u32 v[32:33], s[0:1], v54, s4, v[0:1]
	ds_read_b128 v[32:35], v32
	v_mad_i64_i32 v[54:55], s[0:1], v54, s5, v[6:7]
	v_add_u32_e32 v36, 0x600, v10
	v_ashrrev_i32_e32 v56, 4, v36
	v_mad_u64_u32 v[36:37], s[0:1], v56, s4, v[0:1]
	ds_read_b128 v[36:39], v36
	v_mad_i64_i32 v[56:57], s[0:1], v56, s5, v[6:7]
	v_add_u32_e32 v40, 0x700, v10
	v_ashrrev_i32_e32 v58, 4, v40
	v_mad_u64_u32 v[40:41], s[0:1], v58, s4, v[0:1]
	ds_read_b128 v[40:43], v40
	v_mad_i64_i32 v[6:7], s[0:1], v58, s5, v[6:7]
	s_waitcnt lgkmcnt(7)
	global_store_dwordx4 v[8:9], v[2:5], off
	s_waitcnt lgkmcnt(6)
	global_store_dwordx4 v[46:47], v[16:19], off
	s_waitcnt lgkmcnt(5)
	global_store_dwordx4 v[48:49], v[20:23], off
	s_waitcnt lgkmcnt(4)
	global_store_dwordx4 v[50:51], v[24:27], off
	s_waitcnt lgkmcnt(3)
	global_store_dwordx4 v[52:53], v[28:31], off
	s_waitcnt lgkmcnt(2)
	global_store_dwordx4 v[54:55], v[32:35], off
	s_waitcnt lgkmcnt(1)
	global_store_dwordx4 v[56:57], v[36:39], off
	s_waitcnt lgkmcnt(0)
	global_store_dwordx4 v[6:7], v[40:43], off
	s_nop 1
	s_branch .LBB0_196
